# GEMM1 gate epilogue: the four lower-bound quads of a wave tile loaded together at the first column block (blocks 2-4 no longer load and drain vmcnt(0))
# speedup vs baseline: 1.0083x; 1.0083x over previous
.LBB0_143:
	s_add_i32 s6, s6, s50
	v_add_u32_e32 v131, s6, v213
	v_ashrrev_i32_e32 v133, 11, v131
	v_cmp_lt_u32_e32 vcc, s24, v131
	v_cmp_ne_u32_e64 s[0:1], 4, v133
	s_mov_b32 s52, s7
	v_and_b32_e32 v130, 0x7ff, v131
	s_and_b64 s[44:45], vcc, s[0:1]
	s_and_saveexec_b64 s[0:1], s[44:45]
	s_xor_b64 s[0:1], exec, s[0:1]
	s_cbranch_execz .LBB0_147
	v_cmp_ne_u32_e32 vcc, 3, v133
	s_and_saveexec_b64 s[2:3], vcc
	s_cbranch_execz .LBB0_146
	v_and_b32_e32 v128, 0xfffff800, v131
	v_add_u32_e32 v128, 0xfffff800, v128
	v_ashrrev_i32_e32 v129, 31, v128
	v_lshl_add_u64 v[128:129], v[128:129], 2, s[90:91]
	v_lshlrev_b32_e32 v176, 2, v130
	v_lshl_add_u64 v[128:129], v[128:129], 0, v[176:177]
	global_load_dwordx4 v[134:137], v[128:129], off
	global_load_dwordx4 v[148:151], v[128:129], off offset:64
	global_load_dwordx4 v[152:155], v[128:129], off offset:128
	global_load_dwordx4 v[156:159], v[128:129], off offset:192
	v_mul_f32_e32 v124, 0xbfb8aa3b, v124
	v_exp_f32_e32 v124, v124
	v_mul_f32_e32 v125, 0xbfb8aa3b, v125
	v_exp_f32_e32 v125, v125
	v_mul_f32_e32 v126, 0xbfb8aa3b, v126
	v_exp_f32_e32 v126, v126
	v_mul_f32_e32 v127, 0xbfb8aa3b, v127
	v_exp_f32_e32 v127, v127
	v_add_f32_e32 v124, 1.0, v124
	v_rcp_f32_e32 v124, v124
	v_add_f32_e32 v125, 1.0, v125
	v_rcp_f32_e32 v125, v125
	v_add_f32_e32 v126, 1.0, v126
	v_rcp_f32_e32 v126, v126
	v_add_f32_e32 v127, 1.0, v127
	v_rcp_f32_e32 v127, v127
	s_waitcnt vmcnt(0)
	v_mov_b64_e32 v[144:145], v[134:135]
	v_mov_b64_e32 v[146:147], v[136:137]
	v_sub_f32_e32 v128, 1.0, v134
	v_fma_f32 v124, v124, v128, v134
	v_sub_f32_e32 v128, 1.0, v135
	v_fma_f32 v125, v125, v128, v135
	v_sub_f32_e32 v128, 1.0, v136
	v_fma_f32 v126, v126, v128, v136
	v_sub_f32_e32 v128, 1.0, v137
	v_fmac_f32_e32 v137, v127, v128
	v_log_f32_e32 v124, v124
	v_log_f32_e32 v125, v125
	v_log_f32_e32 v126, v126
	v_log_f32_e32 v127, v137
	v_pk_mul_f32 v[124:125], v[124:125], s[96:97] op_sel_hi:[1,0]
	v_pk_mul_f32 v[126:127], v[126:127], s[96:97] op_sel_hi:[1,0]

.LBB0_149:
	s_or_b64 exec, exec, s[0:1]
	v_add_u32_e32 v134, 16, v131
	v_ashrrev_i32_e32 v135, 11, v134
	v_cmp_lt_u32_e32 vcc, s24, v134
	v_cmp_ne_u32_e64 s[0:1], 4, v135
	v_and_b32_e32 v132, 0x7ff, v134
	s_and_b64 s[46:47], vcc, s[0:1]
	s_and_saveexec_b64 s[0:1], s[46:47]
	s_xor_b64 s[0:1], exec, s[0:1]
	s_cbranch_execz .LBB0_153
	v_cmp_ne_u32_e32 vcc, 3, v135
	s_and_saveexec_b64 s[2:3], vcc
	s_cbranch_execz .LBB0_152
	v_and_b32_e32 v128, 0xfffff800, v134
	v_add_u32_e32 v128, 0xfffff800, v128
	v_ashrrev_i32_e32 v129, 31, v128
	v_lshl_add_u64 v[128:129], v[128:129], 2, s[90:91]
	v_lshlrev_b32_e32 v176, 2, v132
	v_lshl_add_u64 v[128:129], v[128:129], 0, v[176:177]
	v_mov_b64_e32 v[136:137], v[148:149]
	v_mov_b64_e32 v[138:139], v[150:151]
	v_mul_f32_e32 v120, 0xbfb8aa3b, v120
	v_exp_f32_e32 v120, v120
	v_mul_f32_e32 v121, 0xbfb8aa3b, v121
	v_exp_f32_e32 v121, v121
	v_mul_f32_e32 v122, 0xbfb8aa3b, v122
	v_exp_f32_e32 v122, v122
	v_mul_f32_e32 v123, 0xbfb8aa3b, v123
	v_exp_f32_e32 v123, v123
	v_add_f32_e32 v120, 1.0, v120
	v_rcp_f32_e32 v120, v120
	v_add_f32_e32 v121, 1.0, v121
	v_rcp_f32_e32 v121, v121
	v_add_f32_e32 v122, 1.0, v122
	v_rcp_f32_e32 v122, v122
	v_add_f32_e32 v123, 1.0, v123
	v_rcp_f32_e32 v123, v123
	v_sub_f32_e32 v128, 1.0, v136
	v_fma_f32 v120, v120, v128, v136
	v_sub_f32_e32 v128, 1.0, v137
	v_fma_f32 v121, v121, v128, v137
	v_sub_f32_e32 v128, 1.0, v138
	v_fma_f32 v122, v122, v128, v138
	v_sub_f32_e32 v128, 1.0, v139
	v_fmac_f32_e32 v139, v123, v128
	v_log_f32_e32 v120, v120
	v_log_f32_e32 v121, v121
	v_log_f32_e32 v122, v122
	v_log_f32_e32 v123, v139
	v_pk_mul_f32 v[120:121], v[120:121], s[96:97] op_sel_hi:[1,0]
	v_pk_mul_f32 v[122:123], v[122:123], s[96:97] op_sel_hi:[1,0]

.LBB0_155:
	s_or_b64 exec, exec, s[0:1]
	v_cvt_pk_bf16_f32 v138, v120, v121
	v_add_u32_e32 v120, s6, v215
	v_add_u32_e32 v128, s48, v214
	v_cvt_pk_bf16_f32 v139, v122, v123
	v_ashrrev_i32_e32 v122, 11, v120
	v_ashrrev_i32_e32 v129, 31, v128
	v_cvt_pk_bf16_f32 v136, v124, v125
	v_and_b32_e32 v124, 0x7ff, v120
	v_mul_hi_i32_i24_e32 v121, 0x4400, v122
	v_mul_i32_i24_e32 v120, 0x4400, v122
	v_lshl_add_u64 v[122:123], v[120:121], 0, v[128:129]
	v_lshlrev_b64 v[122:123], 12, v[122:123]
	v_cvt_pk_bf16_f32 v137, v126, v127
	v_lshl_add_u64 v[122:123], s[86:87], 0, v[122:123]
	v_lshlrev_b32_e32 v176, 1, v124
	v_permlane16_swap_b32_e32 v136, v138
	v_permlane16_swap_b32_e32 v137, v139
	v_lshl_add_u64 v[122:123], v[122:123], 0, v[176:177]
	s_add_i32 s6, s6, 32
	global_store_dwordx4 v[122:123], v[136:139], off
	v_add_u32_e32 v123, s6, v213
	v_ashrrev_i32_e32 v126, 11, v123
	v_cmp_lt_u32_e32 vcc, s24, v123
	v_cmp_ne_u32_e64 s[0:1], 4, v126
	v_and_b32_e32 v122, 0x7ff, v123
	s_and_b64 s[48:49], vcc, s[0:1]
	s_and_saveexec_b64 s[0:1], s[48:49]
	s_xor_b64 s[0:1], exec, s[0:1]
	s_cbranch_execz .LBB0_159
	v_cmp_ne_u32_e32 vcc, 3, v126
	s_and_saveexec_b64 s[2:3], vcc
	s_cbranch_execz .LBB0_158
	v_and_b32_e32 v124, 0xfffff800, v123
	v_add_u32_e32 v124, 0xfffff800, v124
	v_ashrrev_i32_e32 v125, 31, v124
	v_lshl_add_u64 v[124:125], v[124:125], 2, s[90:91]
	v_lshlrev_b32_e32 v136, 2, v122
	v_mov_b32_e32 v137, v177
	v_lshl_add_u64 v[124:125], v[124:125], 0, v[136:137]
	v_mov_b64_e32 v[136:137], v[152:153]
	v_mov_b64_e32 v[138:139], v[154:155]
	v_mul_f32_e32 v116, 0xbfb8aa3b, v116
	v_exp_f32_e32 v116, v116
	v_mul_f32_e32 v117, 0xbfb8aa3b, v117
	v_exp_f32_e32 v117, v117
	v_mul_f32_e32 v118, 0xbfb8aa3b, v118
	v_exp_f32_e32 v118, v118
	v_mul_f32_e32 v119, 0xbfb8aa3b, v119
	v_exp_f32_e32 v119, v119
	v_add_f32_e32 v116, 1.0, v116
	v_rcp_f32_e32 v116, v116
	v_add_f32_e32 v117, 1.0, v117
	v_rcp_f32_e32 v117, v117
	v_add_f32_e32 v118, 1.0, v118
	v_rcp_f32_e32 v118, v118
	v_add_f32_e32 v119, 1.0, v119
	v_rcp_f32_e32 v119, v119
	v_sub_f32_e32 v124, 1.0, v136
	v_fma_f32 v116, v116, v124, v136
	v_sub_f32_e32 v124, 1.0, v137
	v_fma_f32 v117, v117, v124, v137
	v_sub_f32_e32 v124, 1.0, v138
	v_fma_f32 v118, v118, v124, v138
	v_sub_f32_e32 v124, 1.0, v139
	v_fmac_f32_e32 v139, v119, v124
	v_log_f32_e32 v116, v116
	v_log_f32_e32 v117, v117
	v_log_f32_e32 v118, v118
	v_log_f32_e32 v119, v139
	v_pk_mul_f32 v[116:117], v[116:117], s[96:97] op_sel_hi:[1,0]
	v_pk_mul_f32 v[118:119], v[118:119], s[96:97] op_sel_hi:[1,0]

.LBB0_161:
	s_or_b64 exec, exec, s[0:1]
	v_add_u32_e32 v125, 16, v123
	v_ashrrev_i32_e32 v127, 11, v125
	v_cmp_lt_u32_e32 vcc, s24, v125
	v_cmp_ne_u32_e64 s[0:1], 4, v127
	v_and_b32_e32 v124, 0x7ff, v125
	s_and_b64 s[0:1], vcc, s[0:1]
	s_and_saveexec_b64 s[2:3], s[0:1]
	s_xor_b64 s[2:3], exec, s[2:3]
	s_cbranch_execz .LBB0_165
	v_cmp_ne_u32_e32 vcc, 3, v127
	s_and_saveexec_b64 s[8:9], vcc
	s_cbranch_execz .LBB0_164
	v_and_b32_e32 v136, 0xfffff800, v125
	v_add_u32_e32 v136, 0xfffff800, v136
	v_ashrrev_i32_e32 v137, 31, v136
	v_lshl_add_u64 v[136:137], v[136:137], 2, s[90:91]
	v_lshlrev_b32_e32 v138, 2, v124
	v_mov_b32_e32 v139, v177
	v_lshl_add_u64 v[136:137], v[136:137], 0, v[138:139]
	v_mov_b64_e32 v[136:137], v[156:157]
	v_mov_b64_e32 v[138:139], v[158:159]
	v_mul_f32_e32 v112, 0xbfb8aa3b, v112
	v_exp_f32_e32 v112, v112
	v_mul_f32_e32 v113, 0xbfb8aa3b, v113
	v_exp_f32_e32 v113, v113
	v_mul_f32_e32 v114, 0xbfb8aa3b, v114
	v_exp_f32_e32 v114, v114
	v_mul_f32_e32 v115, 0xbfb8aa3b, v115
	v_exp_f32_e32 v115, v115
	v_add_f32_e32 v112, 1.0, v112
	v_rcp_f32_e32 v112, v112
	v_add_f32_e32 v113, 1.0, v113
	v_rcp_f32_e32 v113, v113
	v_add_f32_e32 v114, 1.0, v114
	v_rcp_f32_e32 v114, v114
	v_add_f32_e32 v115, 1.0, v115
	v_rcp_f32_e32 v115, v115
	v_sub_f32_e32 v140, 1.0, v136
	v_fma_f32 v112, v112, v140, v136
	v_sub_f32_e32 v136, 1.0, v137
	v_fma_f32 v113, v113, v136, v137
	v_sub_f32_e32 v136, 1.0, v138
	v_fma_f32 v114, v114, v136, v138
	v_sub_f32_e32 v136, 1.0, v139
	v_fmac_f32_e32 v139, v115, v136
	v_log_f32_e32 v112, v112
	v_log_f32_e32 v113, v113
	v_log_f32_e32 v114, v114
	v_log_f32_e32 v115, v139
	v_pk_mul_f32 v[112:113], v[112:113], s[96:97] op_sel_hi:[1,0]
	v_pk_mul_f32 v[114:115], v[114:115], s[96:97] op_sel_hi:[1,0]
